# attention loop: per-section s_setprio flips removed
# speedup vs baseline: 1.0090x; 1.0090x over previous
.LBB0_267:
	s_bitcmp1_b32 s4, 0
	s_cselect_b32 s5, 0x8c00, 0
	v_xor_b32_e32 v66, 0x80000000, v154
	s_nop 0
	v_or_b32_e32 v67, s5, v146
	v_add_u32_e32 v172, v67, v183
	ds_read_b128 v[206:209], v172
	ds_read_b128 v[210:213], v172 offset:4608
	ds_read_b128 v[222:225], v172 offset:32
	ds_read_b128 v[238:241], v172 offset:4640
	ds_read_b128 v[242:245], v172 offset:64
	v_mov_b32_e32 v67, v66
	v_mov_b32_e32 v68, v66
	v_mov_b32_e32 v69, v66
	v_mov_b32_e32 v70, v66
	v_mov_b32_e32 v71, v66
	v_mov_b32_e32 v72, v66
	v_mov_b32_e32 v73, v66
	v_mov_b32_e32 v74, v66
	v_mov_b32_e32 v75, v66
	v_mov_b32_e32 v76, v66
	v_mov_b32_e32 v77, v66
	v_mov_b32_e32 v78, v66
	v_mov_b32_e32 v79, v66
	v_mov_b32_e32 v80, v66
	v_mov_b32_e32 v81, v66
	s_waitcnt lgkmcnt(4)
	s_nop 0
	v_mfma_f32_32x32x16_bf16 v[82:97], v[206:209], v[98:101], v[66:81]
	ds_read_b128 v[206:209], v172 offset:4672
	s_waitcnt lgkmcnt(4)
	v_mfma_f32_32x32x16_bf16 v[66:81], v[210:213], v[98:101], v[66:81]
	ds_read_b128 v[210:213], v172 offset:96
	s_waitcnt lgkmcnt(4)
	v_mfma_f32_32x32x16_bf16 v[82:97], v[222:225], v[102:105], v[82:97]
	ds_read_b128 v[222:225], v172 offset:4704
	s_waitcnt lgkmcnt(4)
	v_mfma_f32_32x32x16_bf16 v[66:81], v[238:241], v[102:105], v[66:81]
	s_waitcnt lgkmcnt(3)
	v_mfma_f32_32x32x16_bf16 v[82:97], v[242:245], v[106:109], v[82:97]
	s_waitcnt lgkmcnt(2)
	v_mfma_f32_32x32x16_bf16 v[66:81], v[206:209], v[106:109], v[66:81]
	s_waitcnt lgkmcnt(1)
	v_mfma_f32_32x32x16_bf16 v[82:97], v[210:213], v[110:113], v[82:97]
	s_waitcnt lgkmcnt(0)
	v_mfma_f32_32x32x16_bf16 v[66:81], v[222:225], v[110:113], v[66:81]
	s_nop 0
	s_mov_b64 s[20:21], 0x2000
	v_lshl_add_u64 v[156:157], v[156:157], 0, s[20:21]
	v_lshl_add_u64 v[158:159], v[158:159], 0, s[20:21]
	s_mov_b64 s[20:21], 0x80
	v_lshl_add_u64 v[160:161], v[160:161], 0, s[20:21]
	v_lshl_add_u64 v[162:163], v[162:163], 0, s[20:21]
	v_lshl_add_u64 v[164:165], v[164:165], 0, s[20:21]
	v_lshl_add_u64 v[166:167], v[166:167], 0, s[20:21]
	s_nop 3
	v_max3_f32 v168, v66, v67, v68
	v_max3_f32 v169, v69, v70, v71
	v_max3_f32 v168, v168, v72, v73
	v_max3_f32 v169, v169, v74, v75
	v_max3_f32 v168, v168, v76, v77
	v_max3_f32 v169, v169, v78, v79
	v_max3_f32 v168, v168, v80, v81
	v_max3_f32 v169, v169, v82, v83
	v_max3_f32 v168, v168, v84, v85
	v_max3_f32 v169, v169, v86, v87
	v_max3_f32 v168, v168, v88, v89
	v_max3_f32 v169, v169, v90, v91
	v_max3_f32 v168, v168, v92, v93
	v_max3_f32 v169, v169, v94, v95
	v_max3_f32 v168, v168, v96, v97
	v_max_f32_e32 v168, v168, v169
	v_mov_b32_e32 v169, v168
	s_mov_b32 s20, 0x41000000
	s_nop 1
	v_permlane32_swap_b32_e32 v168, v169
	v_max_f32_e32 v168, v168, v169
	v_cmp_lt_f32_e32 vcc, s20, v168
	s_cbranch_vccz .LBB0_269
	v_max_f32_e32 v168, v168, v168
	v_max_f32_e32 v168, 0, v168
	v_add_f32_e32 v169, v154, v168
	v_sub_f32_e32 v154, v169, v154
	v_mov_b32_e32 v170, v82
	v_mov_b32_e32 v171, v66
	v_mov_b32_e32 v82, v83
	v_mov_b32_e32 v83, v84
	v_mov_b32_e32 v66, v67
	v_mov_b32_e32 v67, v68
	v_pk_add_f32 v[172:173], v[82:83], v[154:155] op_sel_hi:[1,0] neg_lo:[0,1] neg_hi:[0,1]
	v_pk_add_f32 v[82:83], v[66:67], v[154:155] op_sel_hi:[1,0] neg_lo:[0,1] neg_hi:[0,1]
	v_mov_b32_e32 v66, v85
	v_mov_b32_e32 v67, v86
	v_pk_add_f32 v[174:175], v[66:67], v[154:155] op_sel_hi:[1,0] neg_lo:[0,1] neg_hi:[0,1]
	v_mov_b32_e32 v66, v69
	v_mov_b32_e32 v67, v70
	v_pk_add_f32 v[84:85], v[66:67], v[154:155] op_sel_hi:[1,0] neg_lo:[0,1] neg_hi:[0,1]
	v_mov_b32_e32 v66, v87
	v_mov_b32_e32 v67, v88
	v_pk_add_f32 v[176:177], v[66:67], v[154:155] op_sel_hi:[1,0] neg_lo:[0,1] neg_hi:[0,1]
	v_mov_b32_e32 v66, v71
	v_mov_b32_e32 v67, v72
	v_pk_add_f32 v[86:87], v[66:67], v[154:155] op_sel_hi:[1,0] neg_lo:[0,1] neg_hi:[0,1]
	v_mov_b32_e32 v66, v89
	v_mov_b32_e32 v67, v90
	v_pk_add_f32 v[178:179], v[66:67], v[154:155] op_sel_hi:[1,0] neg_lo:[0,1] neg_hi:[0,1]
	v_mov_b32_e32 v66, v73
	v_mov_b32_e32 v67, v74
	v_pk_add_f32 v[88:89], v[66:67], v[154:155] op_sel_hi:[1,0] neg_lo:[0,1] neg_hi:[0,1]
	v_mov_b32_e32 v66, v91
	v_mov_b32_e32 v67, v92
	v_pk_add_f32 v[180:181], v[66:67], v[154:155] op_sel_hi:[1,0] neg_lo:[0,1] neg_hi:[0,1]
	v_mov_b32_e32 v66, v75
	v_mov_b32_e32 v67, v76
	v_pk_add_f32 v[90:91], v[66:67], v[154:155] op_sel_hi:[1,0] neg_lo:[0,1] neg_hi:[0,1]
	v_mov_b32_e32 v66, v93
	v_mov_b32_e32 v67, v94
	v_exp_f32_e64 v168, -v154
	v_pk_add_f32 v[188:189], v[66:67], v[154:155] op_sel_hi:[1,0] neg_lo:[0,1] neg_hi:[0,1]
	v_mov_b32_e32 v66, v77
	v_mov_b32_e32 v67, v78
	v_pk_add_f32 v[92:93], v[66:67], v[154:155] op_sel_hi:[1,0] neg_lo:[0,1] neg_hi:[0,1]
	v_mov_b32_e32 v66, v95
	v_mov_b32_e32 v67, v96
	v_pk_add_f32 v[190:191], v[66:67], v[154:155] op_sel_hi:[1,0] neg_lo:[0,1] neg_hi:[0,1]
	v_mov_b32_e32 v66, v79
	v_mov_b32_e32 v67, v80
	v_pk_add_f32 v[170:171], v[170:171], v[154:155] op_sel_hi:[1,0] neg_lo:[0,1] neg_hi:[0,1]
	v_pk_add_f32 v[94:95], v[66:67], v[154:155] op_sel_hi:[1,0] neg_lo:[0,1] neg_hi:[0,1]
	v_pk_mul_f32 v[64:65], v[64:65], v[168:169] op_sel_hi:[1,0]
	v_pk_mul_f32 v[62:63], v[62:63], v[168:169] op_sel_hi:[1,0]
	v_pk_mul_f32 v[60:61], v[60:61], v[168:169] op_sel_hi:[1,0]
	v_pk_mul_f32 v[58:59], v[58:59], v[168:169] op_sel_hi:[1,0]
	v_pk_mul_f32 v[56:57], v[56:57], v[168:169] op_sel_hi:[1,0]
	v_pk_mul_f32 v[54:55], v[54:55], v[168:169] op_sel_hi:[1,0]
	v_pk_mul_f32 v[52:53], v[52:53], v[168:169] op_sel_hi:[1,0]
	v_pk_mul_f32 v[50:51], v[50:51], v[168:169] op_sel_hi:[1,0]
	v_pk_mul_f32 v[48:49], v[48:49], v[168:169] op_sel_hi:[1,0]
	v_pk_mul_f32 v[46:47], v[46:47], v[168:169] op_sel_hi:[1,0]
	v_pk_mul_f32 v[44:45], v[44:45], v[168:169] op_sel_hi:[1,0]
	v_pk_mul_f32 v[42:43], v[42:43], v[168:169] op_sel_hi:[1,0]
	v_pk_mul_f32 v[40:41], v[40:41], v[168:169] op_sel_hi:[1,0]
	v_pk_mul_f32 v[38:39], v[38:39], v[168:169] op_sel_hi:[1,0]
	v_pk_mul_f32 v[36:37], v[36:37], v[168:169] op_sel_hi:[1,0]
	v_pk_mul_f32 v[34:35], v[34:35], v[168:169] op_sel_hi:[1,0]
	v_pk_mul_f32 v[32:33], v[32:33], v[168:169] op_sel_hi:[1,0]
	v_pk_mul_f32 v[30:31], v[30:31], v[168:169] op_sel_hi:[1,0]
	v_pk_mul_f32 v[28:29], v[28:29], v[168:169] op_sel_hi:[1,0]
	v_pk_mul_f32 v[26:27], v[26:27], v[168:169] op_sel_hi:[1,0]
	v_pk_mul_f32 v[24:25], v[24:25], v[168:169] op_sel_hi:[1,0]
	v_pk_mul_f32 v[22:23], v[22:23], v[168:169] op_sel_hi:[1,0]
	v_pk_mul_f32 v[20:21], v[20:21], v[168:169] op_sel_hi:[1,0]
	v_pk_mul_f32 v[18:19], v[18:19], v[168:169] op_sel_hi:[1,0]
	v_pk_mul_f32 v[16:17], v[16:17], v[168:169] op_sel_hi:[1,0]
	v_pk_mul_f32 v[14:15], v[14:15], v[168:169] op_sel_hi:[1,0]
	v_pk_mul_f32 v[12:13], v[12:13], v[168:169] op_sel_hi:[1,0]
	v_pk_mul_f32 v[10:11], v[10:11], v[168:169] op_sel_hi:[1,0]
	v_pk_mul_f32 v[8:9], v[8:9], v[168:169] op_sel_hi:[1,0]
	v_pk_mul_f32 v[6:7], v[6:7], v[168:169] op_sel_hi:[1,0]
	v_pk_mul_f32 v[4:5], v[4:5], v[168:169] op_sel_hi:[1,0]
	v_pk_mul_f32 v[2:3], v[2:3], v[168:169] op_sel_hi:[1,0]
	v_sub_f32_e32 v97, v97, v154
	v_sub_f32_e32 v81, v81, v154
	v_mul_f32_e32 v185, v185, v168
	v_mov_b32_e32 v154, v169
	v_mov_b32_e32 v67, v82
	v_mov_b32_e32 v68, v83
	v_mov_b32_e32 v69, v84
	v_mov_b32_e32 v70, v85
	v_mov_b32_e32 v71, v86
	v_mov_b32_e32 v72, v87
	v_mov_b32_e32 v73, v88
	v_mov_b32_e32 v74, v89
	v_mov_b32_e32 v75, v90
	v_mov_b32_e32 v76, v91
	v_mov_b32_e32 v77, v92
	v_mov_b32_e32 v78, v93
	v_mov_b32_e32 v79, v94
	v_mov_b32_e32 v80, v95
	v_mov_b32_e32 v83, v172
	v_mov_b32_e32 v84, v173
	v_mov_b32_e32 v85, v174
	v_mov_b32_e32 v86, v175
	v_mov_b32_e32 v87, v176
	v_mov_b32_e32 v88, v177
	v_mov_b32_e32 v89, v178
	v_mov_b32_e32 v90, v179
	v_mov_b32_e32 v91, v180
	v_mov_b32_e32 v92, v181
	v_mov_b32_e32 v93, v188
	v_mov_b32_e32 v94, v189
	v_mov_b32_e32 v95, v190
	v_mov_b32_e32 v96, v191
	v_mov_b32_e32 v82, v170
	v_mov_b32_e32 v66, v171
.LBB0_269:
	v_exp_f32_e32 v180, v82
	v_exp_f32_e32 v181, v66
	v_exp_f32_e32 v178, v83
	v_exp_f32_e32 v179, v67
	v_exp_f32_e32 v176, v84
	v_exp_f32_e32 v177, v68
	v_exp_f32_e32 v174, v85
	v_exp_f32_e32 v175, v69
	v_exp_f32_e32 v172, v86
	v_exp_f32_e32 v173, v70
	v_exp_f32_e32 v170, v87
	v_exp_f32_e32 v171, v71
	v_exp_f32_e32 v168, v88
	v_exp_f32_e32 v169, v72
	v_exp_f32_e32 v88, v89
	v_exp_f32_e32 v89, v73
	v_exp_f32_e32 v86, v90
	v_exp_f32_e32 v87, v74
	v_exp_f32_e32 v84, v91
	v_exp_f32_e32 v85, v75
	v_exp_f32_e32 v82, v92
	v_exp_f32_e32 v83, v76
	v_exp_f32_e32 v74, v93
	v_exp_f32_e32 v75, v77
	v_exp_f32_e32 v72, v94
	v_exp_f32_e32 v73, v78
	v_exp_f32_e32 v70, v95
	v_exp_f32_e32 v71, v79
	v_exp_f32_e32 v68, v96
	v_exp_f32_e32 v69, v80
	v_exp_f32_e32 v66, v97
	v_exp_f32_e32 v67, v81
	v_cvt_pk_bf16_f32 v76, v180, v178
	v_cvt_pk_bf16_f32 v77, v176, v174
	v_cvt_pk_bf16_f32 v78, v172, v170
	v_cvt_pk_bf16_f32 v79, v168, v88
	v_cvt_pk_bf16_f32 v90, v86, v84
	v_cvt_pk_bf16_f32 v91, v82, v74
	v_cvt_pk_bf16_f32 v92, v72, v70
	v_cvt_pk_bf16_f32 v93, v68, v66
	v_cvt_pk_bf16_f32 v94, v181, v179
	v_cvt_pk_bf16_f32 v95, v177, v175
	v_cvt_pk_bf16_f32 v96, v173, v171
	v_cvt_pk_bf16_f32 v97, v169, v89
	v_cvt_pk_bf16_f32 v188, v87, v85
	v_cvt_pk_bf16_f32 v189, v83, v75
	v_cvt_pk_bf16_f32 v190, v73, v71
	v_cvt_pk_bf16_f32 v191, v69, v67
	s_nop 0
	v_add3_u32 v80, s5, v150, v186
	v_add_u32_e32 v246, 0x4800, v80
	v_add_u32_e32 v247, 0x5800, v80
	v_add_u32_e32 v248, 0x6800, v80
	v_add_u32_e32 v249, 0x7800, v80
	ds_read2_b64 v[192:195], v246 offset0:0 offset1:2
	ds_read2_b64 v[206:209], v247 offset0:32 offset1:34
	ds_read2_b64 v[210:213], v248 offset0:64 offset1:66
	ds_read2_b64 v[222:225], v249 offset0:96 offset1:98
	s_waitcnt lgkmcnt(3)
	v_mfma_f32_32x32x16_bf16 v[50:65], v[192:195], v[76:79], v[50:65]
	ds_read2_b64 v[192:195], v246 offset0:4 offset1:6
	s_add_i32 s5, s4, -1
	s_bitcmp1_b32 s5, 0
	s_cselect_b32 s5, 0x8c00, 0
	v_add_f32_e32 v238, v180, v181
	v_add_f32_e32 v239, v172, v173
	s_waitcnt lgkmcnt(3)
	v_mfma_f32_32x32x16_bf16 v[34:49], v[206:209], v[76:79], v[34:49]
	ds_read2_b64 v[206:209], v247 offset0:36 offset1:38
	v_lshlrev_b32_e32 v250, 1, v153
	v_add3_u32 v250, s5, v250, v152
	v_add_f32_e32 v240, v86, v87
	v_add_f32_e32 v241, v72, v73
	s_waitcnt lgkmcnt(3)
	v_mfma_f32_32x32x16_bf16 v[18:33], v[210:213], v[76:79], v[18:33]
	ds_read2_b64 v[210:213], v248 offset0:68 offset1:70
	s_waitcnt vmcnt(0)
	ds_write_b128 v250, v[114:117]
	v_add_f32_e32 v238, v238, v178
	v_add_f32_e32 v239, v239, v170
	s_waitcnt lgkmcnt(4)
	v_mfma_f32_32x32x16_bf16 v[2:17], v[222:225], v[76:79], v[2:17]
	ds_read2_b64 v[222:225], v249 offset0:100 offset1:102
	ds_write_b128 v250, v[118:121] offset:4608
	v_add_f32_e32 v240, v240, v84
	v_add_f32_e32 v241, v241, v70
	s_waitcnt lgkmcnt(5)
	v_mfma_f32_32x32x16_bf16 v[50:65], v[192:195], v[90:93], v[50:65]
	ds_read2_b64 v[192:195], v246 offset0:8 offset1:10
	ds_write_b128 v250, v[122:125] offset:9216
	v_add_f32_e32 v238, v238, v179
	v_add_f32_e32 v239, v239, v171
	s_waitcnt lgkmcnt(6)
	v_mfma_f32_32x32x16_bf16 v[34:49], v[206:209], v[90:93], v[34:49]
	ds_read2_b64 v[206:209], v247 offset0:40 offset1:42
	ds_write_b128 v250, v[126:129] offset:13824
	v_add_f32_e32 v240, v240, v85
	v_add_f32_e32 v241, v241, v71
	s_waitcnt lgkmcnt(7)
	v_mfma_f32_32x32x16_bf16 v[18:33], v[210:213], v[90:93], v[18:33]
	ds_read2_b64 v[210:213], v248 offset0:72 offset1:74
	v_lshlrev_b32_e32 v251, 1, v182
	v_add3_u32 v251, s5, v251, v152
	v_add_f32_e32 v238, v238, v176
	v_add_f32_e32 v239, v239, v168
	s_waitcnt lgkmcnt(6)
	v_mfma_f32_32x32x16_bf16 v[2:17], v[222:225], v[90:93], v[2:17]
	ds_read2_b64 v[222:225], v249 offset0:104 offset1:106
	v_add_u32_e32 v214, 0x4800, v251
	ds_write2_b64 v214, v[130:131], v[132:133] offset1:1
	v_add_f32_e32 v240, v240, v82
	v_add_f32_e32 v241, v241, v68
	s_waitcnt lgkmcnt(6)
	v_mfma_f32_32x32x16_bf16 v[50:65], v[192:195], v[94:97], v[50:65]
	ds_read2_b64 v[192:195], v246 offset0:12 offset1:14
	v_add_u32_e32 v214, 0x5900, v251
	ds_write2_b64 v214, v[134:135], v[136:137] offset1:1
	v_add_f32_e32 v238, v238, v177
	v_add_f32_e32 v239, v239, v169
	s_waitcnt lgkmcnt(6)
	v_mfma_f32_32x32x16_bf16 v[34:49], v[206:209], v[94:97], v[34:49]
	ds_read2_b64 v[206:209], v247 offset0:44 offset1:46
	v_add_u32_e32 v214, 0x6a00, v251
	ds_write2_b64 v214, v[138:139], v[140:141] offset1:1
	v_add_f32_e32 v240, v240, v83
	v_add_f32_e32 v241, v241, v69
	s_waitcnt lgkmcnt(6)
	v_mfma_f32_32x32x16_bf16 v[18:33], v[210:213], v[94:97], v[18:33]
	ds_read2_b64 v[210:213], v248 offset0:76 offset1:78
	v_add_u32_e32 v214, 0x7b00, v251
	ds_write2_b64 v214, v[142:143], v[144:145] offset1:1
	v_add_f32_e32 v238, v238, v174
	v_add_f32_e32 v239, v239, v88
	s_waitcnt lgkmcnt(7)
	v_mfma_f32_32x32x16_bf16 v[2:17], v[222:225], v[94:97], v[2:17]
	ds_read2_b64 v[222:225], v249 offset0:108 offset1:110
	global_load_dwordx4 v[114:117], v[156:157], off offset:-2048
	global_load_dwordx4 v[118:121], v[156:157], off offset:2048
	v_add_f32_e32 v240, v240, v74
	v_add_f32_e32 v241, v241, v66
	s_waitcnt lgkmcnt(6)
	v_mfma_f32_32x32x16_bf16 v[50:65], v[192:195], v[188:191], v[50:65]
	global_load_dwordx4 v[122:125], v[158:159], off offset:-2048
	global_load_dwordx4 v[126:129], v[158:159], off offset:2048
	v_add_f32_e32 v238, v238, v175
	v_add_f32_e32 v239, v239, v89
	s_waitcnt lgkmcnt(4)
	v_mfma_f32_32x32x16_bf16 v[34:49], v[206:209], v[188:191], v[34:49]
	global_load_dwordx4 v[130:133], v[160:161], off offset:384
	global_load_dwordx4 v[134:137], v[162:163], off offset:384
	v_add_f32_e32 v240, v240, v75
	v_add_f32_e32 v241, v241, v67
	s_waitcnt lgkmcnt(2)
	v_mfma_f32_32x32x16_bf16 v[18:33], v[210:213], v[188:191], v[18:33]
	global_load_dwordx4 v[138:141], v[164:165], off offset:384
	global_load_dwordx4 v[142:145], v[166:167], off offset:384
	v_add_f32_e32 v238, v238, v239
	v_add_f32_e32 v240, v240, v241
	s_waitcnt lgkmcnt(0)
	v_mfma_f32_32x32x16_bf16 v[2:17], v[222:225], v[188:191], v[2:17]
	v_add_f32_e32 v238, v238, v240
	s_nop 0
	s_branch .LBB0_266
